# P2 gelu epilogue: exponent scale folded into the cubic coefficients (one multiply less per element)
# speedup vs baseline: 1.0141x; 1.0016x over previous
; __device__ __forceinline__ unsigned cvt_pk_bf16(float lo, float hi) { unsigned r; asm volatile("v_cvt_pk_bf16_f32 %0, %1, %2" : "=v"(r) : "v"(lo), "v"(hi)); return r; }
; __device__ __forceinline__ float gelu_tanh(float x) {
;     const float t = x * (1.0f + 0.044715f * x * x);
;     const float e = __builtin_amdgcn_exp2f(-2.0f * 0.7978845608028654f * 1.4426950408889634f * t);
;     return x * __builtin_amdgcn_rcpf(1.0f + e);
;     __device__ __forceinline__ void operator()(const f32x4 (&acc)[2][2][4][2], const Unit& u, int wr, int wc, int fr, int fq) const {
;     ...
;         if (u.pn >= 2) {
;             const int col0 = u.pn * BM + wc * 32 + 8 * fq;
; #pragma unroll
;             for (int ai = 0; ai < 2; ++ai)
; #pragma unroll
;                 for (int m = 0; m < 4; ++m) { bf16_t* rowp = Zo + (size_t)(row0 + ai * HALF + m * 16) * NZ + col0;
; #pragma unroll
;                     for (int bj = 0; bj < 2; ++bj) { f32x4 v0 = acc[ai][bj][m][0], v1 = acc[ai][bj][m][1];
; #pragma unroll
;                         for (int e = 0; e < 4; ++e) { v0[e] = gelu_tanh(v0[e]); v1[e] = gelu_tanh(v1[e]); }
;                         u32x4 w; w.x = cvt_pk_bf16(v0[0], v0[1]); w.y = cvt_pk_bf16(v0[2], v0[3]); w.z = cvt_pk_bf16(v1[0], v1[1]); w.w = cvt_pk_bf16(v1[2], v1[3]);
;                         *(u32x4*)(rowp + bj * HALF) = w; } }
.LBB0_189:
	s_and_b64 vcc, exec, s[8:9]
	s_cbranch_vccz .LBB0_273
	v_mov_b32_e32 v240, 0xbdd2d3e8
	v_mov_b32_e32 v241, 0xbdd2d3e8
	v_mov_b32_e32 v242, 0xc0135761
	v_mov_b32_e32 v243, 0xc0135761
	v_mov_b32_e32 v244, 1.0
	v_mov_b32_e32 v245, 1.0
	v_lshl_add_u32 v160, s50, 8, v162
	v_mov_b64_e32 v[158:159], s[20:21]
	v_mad_i64_i32 v[250:251], s[8:9], v160, s69, v[158:159]
	v_lshl_or_b32 v136, s48, 9, v138
	v_lshl_add_u64 v[250:251], v[250:251], 0, v[136:137]
	v_pk_mul_f32 v[232:233], v[124:125], v[240:241]
	v_pk_mul_f32 v[234:235], v[126:127], v[240:241]
	v_pk_mul_f32 v[236:237], v[120:121], v[240:241]
	v_pk_mul_f32 v[238:239], v[122:123], v[240:241]
	v_pk_fma_f32 v[232:233], v[124:125], v[232:233], v[242:243]
	v_pk_fma_f32 v[234:235], v[126:127], v[234:235], v[242:243]
	v_pk_fma_f32 v[236:237], v[120:121], v[236:237], v[242:243]
	v_pk_fma_f32 v[238:239], v[122:123], v[238:239], v[242:243]
	v_pk_mul_f32 v[232:233], v[124:125], v[232:233]
	v_pk_mul_f32 v[234:235], v[126:127], v[234:235]
	v_pk_mul_f32 v[236:237], v[120:121], v[236:237]
	v_pk_mul_f32 v[238:239], v[122:123], v[238:239]
	v_exp_f32_e32 v232, v232
	v_exp_f32_e32 v233, v233
	v_exp_f32_e32 v234, v234
	v_exp_f32_e32 v235, v235
	v_exp_f32_e32 v236, v236
	v_exp_f32_e32 v237, v237
	v_exp_f32_e32 v238, v238
	v_exp_f32_e32 v239, v239
	v_pk_add_f32 v[232:233], v[232:233], v[244:245]
	v_pk_add_f32 v[234:235], v[234:235], v[244:245]
	v_pk_add_f32 v[236:237], v[236:237], v[244:245]
	v_pk_add_f32 v[238:239], v[238:239], v[244:245]
	v_rcp_f32_e32 v232, v232
	v_rcp_f32_e32 v233, v233
	v_rcp_f32_e32 v234, v234
	v_rcp_f32_e32 v235, v235
	v_rcp_f32_e32 v236, v236
	v_rcp_f32_e32 v237, v237
	v_rcp_f32_e32 v238, v238
	v_rcp_f32_e32 v239, v239
	v_pk_mul_f32 v[232:233], v[124:125], v[232:233]
	v_pk_mul_f32 v[234:235], v[126:127], v[234:235]
	v_pk_mul_f32 v[236:237], v[120:121], v[236:237]
	v_pk_mul_f32 v[238:239], v[122:123], v[238:239]
	v_cvt_pk_bf16_f32 v246, v232, v233
	v_cvt_pk_bf16_f32 v247, v234, v235
	v_cvt_pk_bf16_f32 v248, v236, v237
	v_cvt_pk_bf16_f32 v249, v238, v239
	global_store_dwordx4 v[250:251], v[246:249], off
	s_nop 1
	v_pk_mul_f32 v[232:233], v[116:117], v[240:241]
	v_pk_mul_f32 v[234:235], v[118:119], v[240:241]
	v_pk_mul_f32 v[236:237], v[112:113], v[240:241]
	v_pk_mul_f32 v[238:239], v[114:115], v[240:241]
	v_pk_fma_f32 v[232:233], v[116:117], v[232:233], v[242:243]
	v_pk_fma_f32 v[234:235], v[118:119], v[234:235], v[242:243]
	v_pk_fma_f32 v[236:237], v[112:113], v[236:237], v[242:243]
	v_pk_fma_f32 v[238:239], v[114:115], v[238:239], v[242:243]
	v_pk_mul_f32 v[232:233], v[116:117], v[232:233]
	v_pk_mul_f32 v[234:235], v[118:119], v[234:235]
	v_pk_mul_f32 v[236:237], v[112:113], v[236:237]
	v_pk_mul_f32 v[238:239], v[114:115], v[238:239]
	v_exp_f32_e32 v232, v232
	v_exp_f32_e32 v233, v233
	v_exp_f32_e32 v234, v234
	v_exp_f32_e32 v235, v235
	v_exp_f32_e32 v236, v236
	v_exp_f32_e32 v237, v237
	v_exp_f32_e32 v238, v238
	v_exp_f32_e32 v239, v239
	v_pk_add_f32 v[232:233], v[232:233], v[244:245]
	v_pk_add_f32 v[234:235], v[234:235], v[244:245]
	v_pk_add_f32 v[236:237], v[236:237], v[244:245]
	v_pk_add_f32 v[238:239], v[238:239], v[244:245]
	v_rcp_f32_e32 v232, v232
	v_rcp_f32_e32 v233, v233
	v_rcp_f32_e32 v234, v234
	v_rcp_f32_e32 v235, v235
	v_rcp_f32_e32 v236, v236
	v_rcp_f32_e32 v237, v237
	v_rcp_f32_e32 v238, v238
	v_rcp_f32_e32 v239, v239
	v_pk_mul_f32 v[232:233], v[116:117], v[232:233]
	v_pk_mul_f32 v[234:235], v[118:119], v[234:235]
	v_pk_mul_f32 v[236:237], v[112:113], v[236:237]
	v_pk_mul_f32 v[238:239], v[114:115], v[238:239]
	v_cvt_pk_bf16_f32 v246, v232, v233
	v_cvt_pk_bf16_f32 v247, v234, v235
	v_cvt_pk_bf16_f32 v248, v236, v237
	v_cvt_pk_bf16_f32 v249, v238, v239
	global_store_dwordx4 v[250:251], v[246:249], off offset:256
	v_or_b32_e32 v250, 16, v160
	v_mad_i64_i32 v[250:251], s[8:9], v250, s69, v[158:159]
	v_lshl_add_u64 v[250:251], v[250:251], 0, v[136:137]
	v_pk_mul_f32 v[232:233], v[108:109], v[240:241]
	v_pk_mul_f32 v[234:235], v[110:111], v[240:241]
	v_pk_mul_f32 v[236:237], v[104:105], v[240:241]
	v_pk_mul_f32 v[238:239], v[106:107], v[240:241]
	v_pk_fma_f32 v[232:233], v[108:109], v[232:233], v[242:243]
	v_pk_fma_f32 v[234:235], v[110:111], v[234:235], v[242:243]
	v_pk_fma_f32 v[236:237], v[104:105], v[236:237], v[242:243]
	v_pk_fma_f32 v[238:239], v[106:107], v[238:239], v[242:243]
	v_pk_mul_f32 v[232:233], v[108:109], v[232:233]
	v_pk_mul_f32 v[234:235], v[110:111], v[234:235]
	v_pk_mul_f32 v[236:237], v[104:105], v[236:237]
	v_pk_mul_f32 v[238:239], v[106:107], v[238:239]
	v_exp_f32_e32 v232, v232
	v_exp_f32_e32 v233, v233
	v_exp_f32_e32 v234, v234
	v_exp_f32_e32 v235, v235
	v_exp_f32_e32 v236, v236
	v_exp_f32_e32 v237, v237
	v_exp_f32_e32 v238, v238
	v_exp_f32_e32 v239, v239
	v_pk_add_f32 v[232:233], v[232:233], v[244:245]
	v_pk_add_f32 v[234:235], v[234:235], v[244:245]
	v_pk_add_f32 v[236:237], v[236:237], v[244:245]
	v_pk_add_f32 v[238:239], v[238:239], v[244:245]
	v_rcp_f32_e32 v232, v232
	v_rcp_f32_e32 v233, v233
	v_rcp_f32_e32 v234, v234
	v_rcp_f32_e32 v235, v235
	v_rcp_f32_e32 v236, v236
	v_rcp_f32_e32 v237, v237
	v_rcp_f32_e32 v238, v238
	v_rcp_f32_e32 v239, v239
	v_pk_mul_f32 v[232:233], v[108:109], v[232:233]
	v_pk_mul_f32 v[234:235], v[110:111], v[234:235]
	v_pk_mul_f32 v[236:237], v[104:105], v[236:237]
	v_pk_mul_f32 v[238:239], v[106:107], v[238:239]
	v_cvt_pk_bf16_f32 v246, v232, v233
	v_cvt_pk_bf16_f32 v247, v234, v235
	v_cvt_pk_bf16_f32 v248, v236, v237
	v_cvt_pk_bf16_f32 v249, v238, v239
	global_store_dwordx4 v[250:251], v[246:249], off
	s_nop 1
	v_pk_mul_f32 v[232:233], v[100:101], v[240:241]
	v_pk_mul_f32 v[234:235], v[102:103], v[240:241]
; __device__ __forceinline__ unsigned cvt_pk_bf16(float lo, float hi) { unsigned r; asm volatile("v_cvt_pk_bf16_f32 %0, %1, %2" : "=v"(r) : "v"(lo), "v"(hi)); return r; }
; __device__ __forceinline__ float gelu_tanh(float x) {
;     const float t = x * (1.0f + 0.044715f * x * x);
;     const float e = __builtin_amdgcn_exp2f(-2.0f * 0.7978845608028654f * 1.4426950408889634f * t);
;     return x * __builtin_amdgcn_rcpf(1.0f + e);
;     __device__ __forceinline__ void operator()(const f32x4 (&acc)[2][2][4][2], const Unit& u, int wr, int wc, int fr, int fq) const {
;     ...
;         if (u.pn >= 2) {
;             const int col0 = u.pn * BM + wc * 32 + 8 * fq;
; #pragma unroll
;             for (int ai = 0; ai < 2; ++ai)
; #pragma unroll
;                 for (int m = 0; m < 4; ++m) { bf16_t* rowp = Zo + (size_t)(row0 + ai * HALF + m * 16) * NZ + col0;
; #pragma unroll
;                     for (int bj = 0; bj < 2; ++bj) { f32x4 v0 = acc[ai][bj][m][0], v1 = acc[ai][bj][m][1];
; #pragma unroll
;                         for (int e = 0; e < 4; ++e) { v0[e] = gelu_tanh(v0[e]); v1[e] = gelu_tanh(v1[e]); }
;                         u32x4 w; w.x = cvt_pk_bf16(v0[0], v0[1]); w.y = cvt_pk_bf16(v0[2], v0[3]); w.z = cvt_pk_bf16(v1[0], v1[1]); w.w = cvt_pk_bf16(v1[2], v1[3]);
;                         *(u32x4*)(rowp + bj * HALF) = w; } }
	v_pk_mul_f32 v[236:237], v[96:97], v[240:241]
	v_pk_mul_f32 v[238:239], v[98:99], v[240:241]
	v_pk_fma_f32 v[232:233], v[100:101], v[232:233], v[242:243]
	v_pk_fma_f32 v[234:235], v[102:103], v[234:235], v[242:243]
	v_pk_fma_f32 v[236:237], v[96:97], v[236:237], v[242:243]
	v_pk_fma_f32 v[238:239], v[98:99], v[238:239], v[242:243]
	v_pk_mul_f32 v[232:233], v[100:101], v[232:233]
	v_pk_mul_f32 v[234:235], v[102:103], v[234:235]
	v_pk_mul_f32 v[236:237], v[96:97], v[236:237]
	v_pk_mul_f32 v[238:239], v[98:99], v[238:239]
	v_exp_f32_e32 v232, v232
	v_exp_f32_e32 v233, v233
	v_exp_f32_e32 v234, v234
	v_exp_f32_e32 v235, v235
	v_exp_f32_e32 v236, v236
	v_exp_f32_e32 v237, v237
	v_exp_f32_e32 v238, v238
	v_exp_f32_e32 v239, v239
	v_pk_add_f32 v[232:233], v[232:233], v[244:245]
	v_pk_add_f32 v[234:235], v[234:235], v[244:245]
	v_pk_add_f32 v[236:237], v[236:237], v[244:245]
	v_pk_add_f32 v[238:239], v[238:239], v[244:245]
	v_rcp_f32_e32 v232, v232
	v_rcp_f32_e32 v233, v233
	v_rcp_f32_e32 v234, v234
	v_rcp_f32_e32 v235, v235
	v_rcp_f32_e32 v236, v236
	v_rcp_f32_e32 v237, v237
	v_rcp_f32_e32 v238, v238
	v_rcp_f32_e32 v239, v239
	v_pk_mul_f32 v[232:233], v[100:101], v[232:233]
	v_pk_mul_f32 v[234:235], v[102:103], v[234:235]
	v_pk_mul_f32 v[236:237], v[96:97], v[236:237]
	v_pk_mul_f32 v[238:239], v[98:99], v[238:239]
	v_cvt_pk_bf16_f32 v246, v232, v233
	v_cvt_pk_bf16_f32 v247, v234, v235
	v_cvt_pk_bf16_f32 v248, v236, v237
	v_cvt_pk_bf16_f32 v249, v238, v239
	global_store_dwordx4 v[250:251], v[246:249], off offset:256
	v_or_b32_e32 v250, 32, v160
	v_mad_i64_i32 v[250:251], s[8:9], v250, s69, v[158:159]
	v_lshl_add_u64 v[250:251], v[250:251], 0, v[136:137]
	v_pk_mul_f32 v[232:233], v[92:93], v[240:241]
	v_pk_mul_f32 v[234:235], v[94:95], v[240:241]
	v_pk_mul_f32 v[236:237], v[88:89], v[240:241]
	v_pk_mul_f32 v[238:239], v[90:91], v[240:241]
	v_pk_fma_f32 v[232:233], v[92:93], v[232:233], v[242:243]
	v_pk_fma_f32 v[234:235], v[94:95], v[234:235], v[242:243]
	v_pk_fma_f32 v[236:237], v[88:89], v[236:237], v[242:243]
	v_pk_fma_f32 v[238:239], v[90:91], v[238:239], v[242:243]
	v_pk_mul_f32 v[232:233], v[92:93], v[232:233]
	v_pk_mul_f32 v[234:235], v[94:95], v[234:235]
	v_pk_mul_f32 v[236:237], v[88:89], v[236:237]
	v_pk_mul_f32 v[238:239], v[90:91], v[238:239]
	v_exp_f32_e32 v232, v232
	v_exp_f32_e32 v233, v233
	v_exp_f32_e32 v234, v234
	v_exp_f32_e32 v235, v235
	v_exp_f32_e32 v236, v236
	v_exp_f32_e32 v237, v237
	v_exp_f32_e32 v238, v238
	v_exp_f32_e32 v239, v239
	v_pk_add_f32 v[232:233], v[232:233], v[244:245]
	v_pk_add_f32 v[234:235], v[234:235], v[244:245]
	v_pk_add_f32 v[236:237], v[236:237], v[244:245]
	v_pk_add_f32 v[238:239], v[238:239], v[244:245]
	v_rcp_f32_e32 v232, v232
	v_rcp_f32_e32 v233, v233
	v_rcp_f32_e32 v234, v234
	v_rcp_f32_e32 v235, v235
	v_rcp_f32_e32 v236, v236
	v_rcp_f32_e32 v237, v237
	v_rcp_f32_e32 v238, v238
	v_rcp_f32_e32 v239, v239
	v_pk_mul_f32 v[232:233], v[92:93], v[232:233]
	v_pk_mul_f32 v[234:235], v[94:95], v[234:235]
	v_pk_mul_f32 v[236:237], v[88:89], v[236:237]
	v_pk_mul_f32 v[238:239], v[90:91], v[238:239]
	v_cvt_pk_bf16_f32 v246, v232, v233
	v_cvt_pk_bf16_f32 v247, v234, v235
	v_cvt_pk_bf16_f32 v248, v236, v237
	v_cvt_pk_bf16_f32 v249, v238, v239
	global_store_dwordx4 v[250:251], v[246:249], off
	s_nop 1
	v_pk_mul_f32 v[232:233], v[84:85], v[240:241]
	v_pk_mul_f32 v[234:235], v[86:87], v[240:241]
	v_pk_mul_f32 v[236:237], v[80:81], v[240:241]
	v_pk_mul_f32 v[238:239], v[82:83], v[240:241]
	v_pk_fma_f32 v[232:233], v[84:85], v[232:233], v[242:243]
	v_pk_fma_f32 v[234:235], v[86:87], v[234:235], v[242:243]
	v_pk_fma_f32 v[236:237], v[80:81], v[236:237], v[242:243]
	v_pk_fma_f32 v[238:239], v[82:83], v[238:239], v[242:243]
	v_pk_mul_f32 v[232:233], v[84:85], v[232:233]
	v_pk_mul_f32 v[234:235], v[86:87], v[234:235]
	v_pk_mul_f32 v[236:237], v[80:81], v[236:237]
	v_pk_mul_f32 v[238:239], v[82:83], v[238:239]
	v_exp_f32_e32 v232, v232
	v_exp_f32_e32 v233, v233
	v_exp_f32_e32 v234, v234
	v_exp_f32_e32 v235, v235
	v_exp_f32_e32 v236, v236
	v_exp_f32_e32 v237, v237
	v_exp_f32_e32 v238, v238
	v_exp_f32_e32 v239, v239
	v_pk_add_f32 v[232:233], v[232:233], v[244:245]
	v_pk_add_f32 v[234:235], v[234:235], v[244:245]
	v_pk_add_f32 v[236:237], v[236:237], v[244:245]
	v_pk_add_f32 v[238:239], v[238:239], v[244:245]
	v_rcp_f32_e32 v232, v232
	v_rcp_f32_e32 v233, v233
	v_rcp_f32_e32 v234, v234
	v_rcp_f32_e32 v235, v235
	v_rcp_f32_e32 v236, v236
	v_rcp_f32_e32 v237, v237
	v_rcp_f32_e32 v238, v238
	v_rcp_f32_e32 v239, v239
	v_pk_mul_f32 v[232:233], v[84:85], v[232:233]
	v_pk_mul_f32 v[234:235], v[86:87], v[234:235]
	v_pk_mul_f32 v[236:237], v[80:81], v[236:237]
	v_pk_mul_f32 v[238:239], v[82:83], v[238:239]
	v_cvt_pk_bf16_f32 v246, v232, v233
	v_cvt_pk_bf16_f32 v247, v234, v235
	v_cvt_pk_bf16_f32 v248, v236, v237
	v_cvt_pk_bf16_f32 v249, v238, v239
	global_store_dwordx4 v[250:251], v[246:249], off offset:256
	v_or_b32_e32 v250, 48, v160
	v_mad_i64_i32 v[250:251], s[8:9], v250, s69, v[158:159]
	v_lshl_add_u64 v[250:251], v[250:251], 0, v[136:137]
	v_pk_mul_f32 v[232:233], v[76:77], v[240:241]
	v_pk_mul_f32 v[234:235], v[78:79], v[240:241]
	v_pk_mul_f32 v[236:237], v[72:73], v[240:241]
	v_pk_mul_f32 v[238:239], v[74:75], v[240:241]
	v_pk_fma_f32 v[232:233], v[76:77], v[232:233], v[242:243]
	v_pk_fma_f32 v[234:235], v[78:79], v[234:235], v[242:243]
	v_pk_fma_f32 v[236:237], v[72:73], v[236:237], v[242:243]
	v_pk_fma_f32 v[238:239], v[74:75], v[238:239], v[242:243]
	v_pk_mul_f32 v[232:233], v[76:77], v[232:233]
	v_pk_mul_f32 v[234:235], v[78:79], v[234:235]
	v_pk_mul_f32 v[236:237], v[72:73], v[236:237]
	v_pk_mul_f32 v[238:239], v[74:75], v[238:239]
; __device__ __forceinline__ unsigned cvt_pk_bf16(float lo, float hi) { unsigned r; asm volatile("v_cvt_pk_bf16_f32 %0, %1, %2" : "=v"(r) : "v"(lo), "v"(hi)); return r; }
; __device__ __forceinline__ float gelu_tanh(float x) {
;     const float t = x * (1.0f + 0.044715f * x * x);
;     const float e = __builtin_amdgcn_exp2f(-2.0f * 0.7978845608028654f * 1.4426950408889634f * t);
;     return x * __builtin_amdgcn_rcpf(1.0f + e);
;     __device__ __forceinline__ void operator()(const f32x4 (&acc)[2][2][4][2], const Unit& u, int wr, int wc, int fr, int fq) const {
;     ...
;         if (u.pn >= 2) {
;             const int col0 = u.pn * BM + wc * 32 + 8 * fq;
; #pragma unroll
;             for (int ai = 0; ai < 2; ++ai)
; #pragma unroll
;                 for (int m = 0; m < 4; ++m) { bf16_t* rowp = Zo + (size_t)(row0 + ai * HALF + m * 16) * NZ + col0;
; #pragma unroll
;                     for (int bj = 0; bj < 2; ++bj) { f32x4 v0 = acc[ai][bj][m][0], v1 = acc[ai][bj][m][1];
; #pragma unroll
;                         for (int e = 0; e < 4; ++e) { v0[e] = gelu_tanh(v0[e]); v1[e] = gelu_tanh(v1[e]); }
;                         u32x4 w; w.x = cvt_pk_bf16(v0[0], v0[1]); w.y = cvt_pk_bf16(v0[2], v0[3]); w.z = cvt_pk_bf16(v1[0], v1[1]); w.w = cvt_pk_bf16(v1[2], v1[3]);
;                         *(u32x4*)(rowp + bj * HALF) = w; } }
	v_exp_f32_e32 v232, v232
	v_exp_f32_e32 v233, v233
	v_exp_f32_e32 v234, v234
	v_exp_f32_e32 v235, v235
	v_exp_f32_e32 v236, v236
	v_exp_f32_e32 v237, v237
	v_exp_f32_e32 v238, v238
	v_exp_f32_e32 v239, v239
	v_pk_add_f32 v[232:233], v[232:233], v[244:245]
	v_pk_add_f32 v[234:235], v[234:235], v[244:245]
	v_pk_add_f32 v[236:237], v[236:237], v[244:245]
	v_pk_add_f32 v[238:239], v[238:239], v[244:245]
	v_rcp_f32_e32 v232, v232
	v_rcp_f32_e32 v233, v233
	v_rcp_f32_e32 v234, v234
	v_rcp_f32_e32 v235, v235
	v_rcp_f32_e32 v236, v236
	v_rcp_f32_e32 v237, v237
	v_rcp_f32_e32 v238, v238
	v_rcp_f32_e32 v239, v239
	v_pk_mul_f32 v[232:233], v[76:77], v[232:233]
	v_pk_mul_f32 v[234:235], v[78:79], v[234:235]
	v_pk_mul_f32 v[236:237], v[72:73], v[236:237]
	v_pk_mul_f32 v[238:239], v[74:75], v[238:239]
	v_cvt_pk_bf16_f32 v246, v232, v233
	v_cvt_pk_bf16_f32 v247, v234, v235
	v_cvt_pk_bf16_f32 v248, v236, v237
	v_cvt_pk_bf16_f32 v249, v238, v239
	global_store_dwordx4 v[250:251], v[246:249], off
	s_nop 1
	v_pk_mul_f32 v[232:233], v[68:69], v[240:241]
	v_pk_mul_f32 v[234:235], v[70:71], v[240:241]
	v_pk_mul_f32 v[236:237], v[64:65], v[240:241]
	v_pk_mul_f32 v[238:239], v[66:67], v[240:241]
	v_pk_fma_f32 v[232:233], v[68:69], v[232:233], v[242:243]
	v_pk_fma_f32 v[234:235], v[70:71], v[234:235], v[242:243]
	v_pk_fma_f32 v[236:237], v[64:65], v[236:237], v[242:243]
	v_pk_fma_f32 v[238:239], v[66:67], v[238:239], v[242:243]
	v_pk_mul_f32 v[232:233], v[68:69], v[232:233]
	v_pk_mul_f32 v[234:235], v[70:71], v[234:235]
	v_pk_mul_f32 v[236:237], v[64:65], v[236:237]
	v_pk_mul_f32 v[238:239], v[66:67], v[238:239]
	v_exp_f32_e32 v232, v232
	v_exp_f32_e32 v233, v233
	v_exp_f32_e32 v234, v234
	v_exp_f32_e32 v235, v235
	v_exp_f32_e32 v236, v236
	v_exp_f32_e32 v237, v237
	v_exp_f32_e32 v238, v238
	v_exp_f32_e32 v239, v239
	v_pk_add_f32 v[232:233], v[232:233], v[244:245]
	v_pk_add_f32 v[234:235], v[234:235], v[244:245]
	v_pk_add_f32 v[236:237], v[236:237], v[244:245]
	v_pk_add_f32 v[238:239], v[238:239], v[244:245]
	v_rcp_f32_e32 v232, v232
	v_rcp_f32_e32 v233, v233
	v_rcp_f32_e32 v234, v234
	v_rcp_f32_e32 v235, v235
	v_rcp_f32_e32 v236, v236
	v_rcp_f32_e32 v237, v237
	v_rcp_f32_e32 v238, v238
	v_rcp_f32_e32 v239, v239
	v_pk_mul_f32 v[232:233], v[68:69], v[232:233]
	v_pk_mul_f32 v[234:235], v[70:71], v[234:235]
	v_pk_mul_f32 v[236:237], v[64:65], v[236:237]
	v_pk_mul_f32 v[238:239], v[66:67], v[238:239]
	v_cvt_pk_bf16_f32 v246, v232, v233
	v_cvt_pk_bf16_f32 v247, v234, v235
	v_cvt_pk_bf16_f32 v248, v236, v237
	v_cvt_pk_bf16_f32 v249, v238, v239
	global_store_dwordx4 v[250:251], v[246:249], off offset:256
	v_add_u32_e32 v250, 0x80, v160
	v_mad_i64_i32 v[250:251], s[8:9], v250, s69, v[158:159]
	v_lshl_add_u64 v[250:251], v[250:251], 0, v[136:137]
	v_pk_mul_f32 v[232:233], v[60:61], v[240:241]
	v_pk_mul_f32 v[234:235], v[62:63], v[240:241]
	v_pk_mul_f32 v[236:237], v[56:57], v[240:241]
	v_pk_mul_f32 v[238:239], v[58:59], v[240:241]
	v_pk_fma_f32 v[232:233], v[60:61], v[232:233], v[242:243]
	v_pk_fma_f32 v[234:235], v[62:63], v[234:235], v[242:243]
	v_pk_fma_f32 v[236:237], v[56:57], v[236:237], v[242:243]
	v_pk_fma_f32 v[238:239], v[58:59], v[238:239], v[242:243]
	v_pk_mul_f32 v[232:233], v[60:61], v[232:233]
	v_pk_mul_f32 v[234:235], v[62:63], v[234:235]
	v_pk_mul_f32 v[236:237], v[56:57], v[236:237]
	v_pk_mul_f32 v[238:239], v[58:59], v[238:239]
	v_exp_f32_e32 v232, v232
	v_exp_f32_e32 v233, v233
	v_exp_f32_e32 v234, v234
	v_exp_f32_e32 v235, v235
	v_exp_f32_e32 v236, v236
	v_exp_f32_e32 v237, v237
	v_exp_f32_e32 v238, v238
	v_exp_f32_e32 v239, v239
	v_pk_add_f32 v[232:233], v[232:233], v[244:245]
	v_pk_add_f32 v[234:235], v[234:235], v[244:245]
	v_pk_add_f32 v[236:237], v[236:237], v[244:245]
	v_pk_add_f32 v[238:239], v[238:239], v[244:245]
	v_rcp_f32_e32 v232, v232
	v_rcp_f32_e32 v233, v233
	v_rcp_f32_e32 v234, v234
	v_rcp_f32_e32 v235, v235
	v_rcp_f32_e32 v236, v236
	v_rcp_f32_e32 v237, v237
	v_rcp_f32_e32 v238, v238
	v_rcp_f32_e32 v239, v239
	v_pk_mul_f32 v[232:233], v[60:61], v[232:233]
	v_pk_mul_f32 v[234:235], v[62:63], v[234:235]
	v_pk_mul_f32 v[236:237], v[56:57], v[236:237]
	v_pk_mul_f32 v[238:239], v[58:59], v[238:239]
	v_cvt_pk_bf16_f32 v246, v232, v233
	v_cvt_pk_bf16_f32 v247, v234, v235
	v_cvt_pk_bf16_f32 v248, v236, v237
	v_cvt_pk_bf16_f32 v249, v238, v239
	global_store_dwordx4 v[250:251], v[246:249], off
	s_nop 1
	v_pk_mul_f32 v[232:233], v[52:53], v[240:241]
	v_pk_mul_f32 v[234:235], v[54:55], v[240:241]
	v_pk_mul_f32 v[236:237], v[48:49], v[240:241]
	v_pk_mul_f32 v[238:239], v[50:51], v[240:241]
	v_pk_fma_f32 v[232:233], v[52:53], v[232:233], v[242:243]
	v_pk_fma_f32 v[234:235], v[54:55], v[234:235], v[242:243]
	v_pk_fma_f32 v[236:237], v[48:49], v[236:237], v[242:243]
	v_pk_fma_f32 v[238:239], v[50:51], v[238:239], v[242:243]
	v_pk_mul_f32 v[232:233], v[52:53], v[232:233]
	v_pk_mul_f32 v[234:235], v[54:55], v[234:235]
	v_pk_mul_f32 v[236:237], v[48:49], v[236:237]
	v_pk_mul_f32 v[238:239], v[50:51], v[238:239]
	v_exp_f32_e32 v232, v232
	v_exp_f32_e32 v233, v233
	v_exp_f32_e32 v234, v234
	v_exp_f32_e32 v235, v235
	v_exp_f32_e32 v236, v236
	v_exp_f32_e32 v237, v237
	v_exp_f32_e32 v238, v238
	v_exp_f32_e32 v239, v239
	v_pk_add_f32 v[232:233], v[232:233], v[244:245]
	v_pk_add_f32 v[234:235], v[234:235], v[244:245]
	v_pk_add_f32 v[236:237], v[236:237], v[244:245]
	v_pk_add_f32 v[238:239], v[238:239], v[244:245]
	v_rcp_f32_e32 v232, v232
	v_rcp_f32_e32 v233, v233
	v_rcp_f32_e32 v234, v234
	v_rcp_f32_e32 v235, v235
	v_rcp_f32_e32 v236, v236
	v_rcp_f32_e32 v237, v237
	v_rcp_f32_e32 v238, v238
	v_rcp_f32_e32 v239, v239
	v_pk_mul_f32 v[232:233], v[52:53], v[232:233]
; __device__ __forceinline__ unsigned cvt_pk_bf16(float lo, float hi) { unsigned r; asm volatile("v_cvt_pk_bf16_f32 %0, %1, %2" : "=v"(r) : "v"(lo), "v"(hi)); return r; }
; __device__ __forceinline__ float gelu_tanh(float x) {
;     const float t = x * (1.0f + 0.044715f * x * x);
;     const float e = __builtin_amdgcn_exp2f(-2.0f * 0.7978845608028654f * 1.4426950408889634f * t);
;     return x * __builtin_amdgcn_rcpf(1.0f + e);
;     __device__ __forceinline__ void operator()(const f32x4 (&acc)[2][2][4][2], const Unit& u, int wr, int wc, int fr, int fq) const {
;     ...
;         if (u.pn >= 2) {
;             const int col0 = u.pn * BM + wc * 32 + 8 * fq;
; #pragma unroll
;             for (int ai = 0; ai < 2; ++ai)
; #pragma unroll
;                 for (int m = 0; m < 4; ++m) { bf16_t* rowp = Zo + (size_t)(row0 + ai * HALF + m * 16) * NZ + col0;
; #pragma unroll
;                     for (int bj = 0; bj < 2; ++bj) { f32x4 v0 = acc[ai][bj][m][0], v1 = acc[ai][bj][m][1];
; #pragma unroll
;                         for (int e = 0; e < 4; ++e) { v0[e] = gelu_tanh(v0[e]); v1[e] = gelu_tanh(v1[e]); }
;                         u32x4 w; w.x = cvt_pk_bf16(v0[0], v0[1]); w.y = cvt_pk_bf16(v0[2], v0[3]); w.z = cvt_pk_bf16(v1[0], v1[1]); w.w = cvt_pk_bf16(v1[2], v1[3]);
;                         *(u32x4*)(rowp + bj * HALF) = w; } }
	v_pk_mul_f32 v[234:235], v[54:55], v[234:235]
	v_pk_mul_f32 v[236:237], v[48:49], v[236:237]
	v_pk_mul_f32 v[238:239], v[50:51], v[238:239]
	v_cvt_pk_bf16_f32 v246, v232, v233
	v_cvt_pk_bf16_f32 v247, v234, v235
	v_cvt_pk_bf16_f32 v248, v236, v237
	v_cvt_pk_bf16_f32 v249, v238, v239
	global_store_dwordx4 v[250:251], v[246:249], off offset:256
	v_add_u32_e32 v250, 0x90, v160
	v_mad_i64_i32 v[250:251], s[8:9], v250, s69, v[158:159]
	v_lshl_add_u64 v[250:251], v[250:251], 0, v[136:137]
	v_pk_mul_f32 v[232:233], v[44:45], v[240:241]
	v_pk_mul_f32 v[234:235], v[46:47], v[240:241]
	v_pk_mul_f32 v[236:237], v[40:41], v[240:241]
	v_pk_mul_f32 v[238:239], v[42:43], v[240:241]
	v_pk_fma_f32 v[232:233], v[44:45], v[232:233], v[242:243]
	v_pk_fma_f32 v[234:235], v[46:47], v[234:235], v[242:243]
	v_pk_fma_f32 v[236:237], v[40:41], v[236:237], v[242:243]
	v_pk_fma_f32 v[238:239], v[42:43], v[238:239], v[242:243]
	v_pk_mul_f32 v[232:233], v[44:45], v[232:233]
	v_pk_mul_f32 v[234:235], v[46:47], v[234:235]
	v_pk_mul_f32 v[236:237], v[40:41], v[236:237]
	v_pk_mul_f32 v[238:239], v[42:43], v[238:239]
	v_exp_f32_e32 v232, v232
	v_exp_f32_e32 v233, v233
	v_exp_f32_e32 v234, v234
	v_exp_f32_e32 v235, v235
	v_exp_f32_e32 v236, v236
	v_exp_f32_e32 v237, v237
	v_exp_f32_e32 v238, v238
	v_exp_f32_e32 v239, v239
	v_pk_add_f32 v[232:233], v[232:233], v[244:245]
	v_pk_add_f32 v[234:235], v[234:235], v[244:245]
	v_pk_add_f32 v[236:237], v[236:237], v[244:245]
	v_pk_add_f32 v[238:239], v[238:239], v[244:245]
	v_rcp_f32_e32 v232, v232
	v_rcp_f32_e32 v233, v233
	v_rcp_f32_e32 v234, v234
	v_rcp_f32_e32 v235, v235
	v_rcp_f32_e32 v236, v236
	v_rcp_f32_e32 v237, v237
	v_rcp_f32_e32 v238, v238
	v_rcp_f32_e32 v239, v239
	v_pk_mul_f32 v[232:233], v[44:45], v[232:233]
	v_pk_mul_f32 v[234:235], v[46:47], v[234:235]
	v_pk_mul_f32 v[236:237], v[40:41], v[236:237]
	v_pk_mul_f32 v[238:239], v[42:43], v[238:239]
	v_cvt_pk_bf16_f32 v246, v232, v233
	v_cvt_pk_bf16_f32 v247, v234, v235
	v_cvt_pk_bf16_f32 v248, v236, v237
	v_cvt_pk_bf16_f32 v249, v238, v239
	global_store_dwordx4 v[250:251], v[246:249], off
	s_nop 1
	v_pk_mul_f32 v[232:233], v[36:37], v[240:241]
	v_pk_mul_f32 v[234:235], v[38:39], v[240:241]
	v_pk_mul_f32 v[236:237], v[32:33], v[240:241]
	v_pk_mul_f32 v[238:239], v[34:35], v[240:241]
	v_pk_fma_f32 v[232:233], v[36:37], v[232:233], v[242:243]
	v_pk_fma_f32 v[234:235], v[38:39], v[234:235], v[242:243]
	v_pk_fma_f32 v[236:237], v[32:33], v[236:237], v[242:243]
	v_pk_fma_f32 v[238:239], v[34:35], v[238:239], v[242:243]
	v_pk_mul_f32 v[232:233], v[36:37], v[232:233]
	v_pk_mul_f32 v[234:235], v[38:39], v[234:235]
	v_pk_mul_f32 v[236:237], v[32:33], v[236:237]
	v_pk_mul_f32 v[238:239], v[34:35], v[238:239]
	v_exp_f32_e32 v232, v232
	v_exp_f32_e32 v233, v233
	v_exp_f32_e32 v234, v234
	v_exp_f32_e32 v235, v235
	v_exp_f32_e32 v236, v236
	v_exp_f32_e32 v237, v237
	v_exp_f32_e32 v238, v238
	v_exp_f32_e32 v239, v239
	v_pk_add_f32 v[232:233], v[232:233], v[244:245]
	v_pk_add_f32 v[234:235], v[234:235], v[244:245]
	v_pk_add_f32 v[236:237], v[236:237], v[244:245]
	v_pk_add_f32 v[238:239], v[238:239], v[244:245]
	v_rcp_f32_e32 v232, v232
	v_rcp_f32_e32 v233, v233
	v_rcp_f32_e32 v234, v234
	v_rcp_f32_e32 v235, v235
	v_rcp_f32_e32 v236, v236
	v_rcp_f32_e32 v237, v237
	v_rcp_f32_e32 v238, v238
	v_rcp_f32_e32 v239, v239
	v_pk_mul_f32 v[232:233], v[36:37], v[232:233]
	v_pk_mul_f32 v[234:235], v[38:39], v[234:235]
	v_pk_mul_f32 v[236:237], v[32:33], v[236:237]
	v_pk_mul_f32 v[238:239], v[34:35], v[238:239]
	v_cvt_pk_bf16_f32 v246, v232, v233
	v_cvt_pk_bf16_f32 v247, v234, v235
	v_cvt_pk_bf16_f32 v248, v236, v237
	v_cvt_pk_bf16_f32 v249, v238, v239
	global_store_dwordx4 v[250:251], v[246:249], off offset:256
	v_add_u32_e32 v250, 0xa0, v160
	v_mad_i64_i32 v[250:251], s[8:9], v250, s69, v[158:159]
	v_lshl_add_u64 v[250:251], v[250:251], 0, v[136:137]
	v_pk_mul_f32 v[232:233], v[28:29], v[240:241]
	v_pk_mul_f32 v[234:235], v[30:31], v[240:241]
	v_pk_mul_f32 v[236:237], v[24:25], v[240:241]
	v_pk_mul_f32 v[238:239], v[26:27], v[240:241]
	v_pk_fma_f32 v[232:233], v[28:29], v[232:233], v[242:243]
	v_pk_fma_f32 v[234:235], v[30:31], v[234:235], v[242:243]
	v_pk_fma_f32 v[236:237], v[24:25], v[236:237], v[242:243]
	v_pk_fma_f32 v[238:239], v[26:27], v[238:239], v[242:243]
	v_pk_mul_f32 v[232:233], v[28:29], v[232:233]
	v_pk_mul_f32 v[234:235], v[30:31], v[234:235]
	v_pk_mul_f32 v[236:237], v[24:25], v[236:237]
	v_pk_mul_f32 v[238:239], v[26:27], v[238:239]
	v_exp_f32_e32 v232, v232
	v_exp_f32_e32 v233, v233
	v_exp_f32_e32 v234, v234
	v_exp_f32_e32 v235, v235
	v_exp_f32_e32 v236, v236
	v_exp_f32_e32 v237, v237
	v_exp_f32_e32 v238, v238
	v_exp_f32_e32 v239, v239
	v_pk_add_f32 v[232:233], v[232:233], v[244:245]
	v_pk_add_f32 v[234:235], v[234:235], v[244:245]
	v_pk_add_f32 v[236:237], v[236:237], v[244:245]
	v_pk_add_f32 v[238:239], v[238:239], v[244:245]
	v_rcp_f32_e32 v232, v232
	v_rcp_f32_e32 v233, v233
	v_rcp_f32_e32 v234, v234
	v_rcp_f32_e32 v235, v235
	v_rcp_f32_e32 v236, v236
	v_rcp_f32_e32 v237, v237
	v_rcp_f32_e32 v238, v238
	v_rcp_f32_e32 v239, v239
	v_pk_mul_f32 v[232:233], v[28:29], v[232:233]
	v_pk_mul_f32 v[234:235], v[30:31], v[234:235]
	v_pk_mul_f32 v[236:237], v[24:25], v[236:237]
	v_pk_mul_f32 v[238:239], v[26:27], v[238:239]
; __device__ __forceinline__ unsigned cvt_pk_bf16(float lo, float hi) { unsigned r; asm volatile("v_cvt_pk_bf16_f32 %0, %1, %2" : "=v"(r) : "v"(lo), "v"(hi)); return r; }
; __device__ __forceinline__ float gelu_tanh(float x) {
;     const float t = x * (1.0f + 0.044715f * x * x);
;     const float e = __builtin_amdgcn_exp2f(-2.0f * 0.7978845608028654f * 1.4426950408889634f * t);
;     return x * __builtin_amdgcn_rcpf(1.0f + e);
;     __device__ __forceinline__ void operator()(const f32x4 (&acc)[2][2][4][2], const Unit& u, int wr, int wc, int fr, int fq) const {
;     ...
;         if (u.pn >= 2) {
;             const int col0 = u.pn * BM + wc * 32 + 8 * fq;
; #pragma unroll
;             for (int ai = 0; ai < 2; ++ai)
; #pragma unroll
;                 for (int m = 0; m < 4; ++m) { bf16_t* rowp = Zo + (size_t)(row0 + ai * HALF + m * 16) * NZ + col0;
; #pragma unroll
;                     for (int bj = 0; bj < 2; ++bj) { f32x4 v0 = acc[ai][bj][m][0], v1 = acc[ai][bj][m][1];
; #pragma unroll
;                         for (int e = 0; e < 4; ++e) { v0[e] = gelu_tanh(v0[e]); v1[e] = gelu_tanh(v1[e]); }
;                         u32x4 w; w.x = cvt_pk_bf16(v0[0], v0[1]); w.y = cvt_pk_bf16(v0[2], v0[3]); w.z = cvt_pk_bf16(v1[0], v1[1]); w.w = cvt_pk_bf16(v1[2], v1[3]);
;                         *(u32x4*)(rowp + bj * HALF) = w; } }
	v_cvt_pk_bf16_f32 v246, v232, v233
	v_cvt_pk_bf16_f32 v247, v234, v235
	v_cvt_pk_bf16_f32 v248, v236, v237
	v_cvt_pk_bf16_f32 v249, v238, v239
	global_store_dwordx4 v[250:251], v[246:249], off
	s_nop 1
	v_pk_mul_f32 v[232:233], v[20:21], v[240:241]
	v_pk_mul_f32 v[234:235], v[22:23], v[240:241]
	v_pk_mul_f32 v[236:237], v[16:17], v[240:241]
	v_pk_mul_f32 v[238:239], v[18:19], v[240:241]
	v_pk_fma_f32 v[232:233], v[20:21], v[232:233], v[242:243]
	v_pk_fma_f32 v[234:235], v[22:23], v[234:235], v[242:243]
	v_pk_fma_f32 v[236:237], v[16:17], v[236:237], v[242:243]
	v_pk_fma_f32 v[238:239], v[18:19], v[238:239], v[242:243]
	v_pk_mul_f32 v[232:233], v[20:21], v[232:233]
	v_pk_mul_f32 v[234:235], v[22:23], v[234:235]
	v_pk_mul_f32 v[236:237], v[16:17], v[236:237]
	v_pk_mul_f32 v[238:239], v[18:19], v[238:239]
	v_exp_f32_e32 v232, v232
	v_exp_f32_e32 v233, v233
	v_exp_f32_e32 v234, v234
	v_exp_f32_e32 v235, v235
	v_exp_f32_e32 v236, v236
	v_exp_f32_e32 v237, v237
	v_exp_f32_e32 v238, v238
	v_exp_f32_e32 v239, v239
	v_pk_add_f32 v[232:233], v[232:233], v[244:245]
	v_pk_add_f32 v[234:235], v[234:235], v[244:245]
	v_pk_add_f32 v[236:237], v[236:237], v[244:245]
	v_pk_add_f32 v[238:239], v[238:239], v[244:245]
	v_rcp_f32_e32 v232, v232
	v_rcp_f32_e32 v233, v233
	v_rcp_f32_e32 v234, v234
	v_rcp_f32_e32 v235, v235
	v_rcp_f32_e32 v236, v236
	v_rcp_f32_e32 v237, v237
	v_rcp_f32_e32 v238, v238
	v_rcp_f32_e32 v239, v239
	v_pk_mul_f32 v[232:233], v[20:21], v[232:233]
	v_pk_mul_f32 v[234:235], v[22:23], v[234:235]
	v_pk_mul_f32 v[236:237], v[16:17], v[236:237]
	v_pk_mul_f32 v[238:239], v[18:19], v[238:239]
	v_cvt_pk_bf16_f32 v246, v232, v233
	v_cvt_pk_bf16_f32 v247, v234, v235
	v_cvt_pk_bf16_f32 v248, v236, v237
	v_cvt_pk_bf16_f32 v249, v238, v239
	global_store_dwordx4 v[250:251], v[246:249], off offset:256
	v_add_u32_e32 v250, 0xb0, v160
	v_mad_i64_i32 v[250:251], s[8:9], v250, s69, v[158:159]
	v_lshl_add_u64 v[250:251], v[250:251], 0, v[136:137]
	v_pk_mul_f32 v[232:233], v[12:13], v[240:241]
	v_pk_mul_f32 v[234:235], v[14:15], v[240:241]
	v_pk_mul_f32 v[236:237], v[8:9], v[240:241]
	v_pk_mul_f32 v[238:239], v[10:11], v[240:241]
	v_pk_fma_f32 v[232:233], v[12:13], v[232:233], v[242:243]
	v_pk_fma_f32 v[234:235], v[14:15], v[234:235], v[242:243]
	v_pk_fma_f32 v[236:237], v[8:9], v[236:237], v[242:243]
	v_pk_fma_f32 v[238:239], v[10:11], v[238:239], v[242:243]
	v_pk_mul_f32 v[232:233], v[12:13], v[232:233]
	v_pk_mul_f32 v[234:235], v[14:15], v[234:235]
	v_pk_mul_f32 v[236:237], v[8:9], v[236:237]
	v_pk_mul_f32 v[238:239], v[10:11], v[238:239]
	v_exp_f32_e32 v232, v232
	v_exp_f32_e32 v233, v233
	v_exp_f32_e32 v234, v234
	v_exp_f32_e32 v235, v235
	v_exp_f32_e32 v236, v236
	v_exp_f32_e32 v237, v237
	v_exp_f32_e32 v238, v238
	v_exp_f32_e32 v239, v239
	v_pk_add_f32 v[232:233], v[232:233], v[244:245]
	v_pk_add_f32 v[234:235], v[234:235], v[244:245]
	v_pk_add_f32 v[236:237], v[236:237], v[244:245]
	v_pk_add_f32 v[238:239], v[238:239], v[244:245]
	v_rcp_f32_e32 v232, v232
	v_rcp_f32_e32 v233, v233
	v_rcp_f32_e32 v234, v234
	v_rcp_f32_e32 v235, v235
	v_rcp_f32_e32 v236, v236
	v_rcp_f32_e32 v237, v237
	v_rcp_f32_e32 v238, v238
	v_rcp_f32_e32 v239, v239
	v_pk_mul_f32 v[232:233], v[12:13], v[232:233]
	v_pk_mul_f32 v[234:235], v[14:15], v[234:235]
	v_pk_mul_f32 v[236:237], v[8:9], v[236:237]
	v_pk_mul_f32 v[238:239], v[10:11], v[238:239]
	v_cvt_pk_bf16_f32 v246, v232, v233
	v_cvt_pk_bf16_f32 v247, v234, v235
	v_cvt_pk_bf16_f32 v248, v236, v237
	v_cvt_pk_bf16_f32 v249, v238, v239
	global_store_dwordx4 v[250:251], v[246:249], off
	s_nop 1
	v_pk_mul_f32 v[232:233], v[4:5], v[240:241]
	v_pk_mul_f32 v[234:235], v[6:7], v[240:241]
	v_pk_mul_f32 v[236:237], v[0:1], v[240:241]
	v_pk_mul_f32 v[238:239], v[2:3], v[240:241]
	v_pk_fma_f32 v[232:233], v[4:5], v[232:233], v[242:243]
	v_pk_fma_f32 v[234:235], v[6:7], v[234:235], v[242:243]
	v_pk_fma_f32 v[236:237], v[0:1], v[236:237], v[242:243]
	v_pk_fma_f32 v[238:239], v[2:3], v[238:239], v[242:243]
	v_pk_mul_f32 v[232:233], v[4:5], v[232:233]
	v_pk_mul_f32 v[234:235], v[6:7], v[234:235]
	v_pk_mul_f32 v[236:237], v[0:1], v[236:237]
	v_pk_mul_f32 v[238:239], v[2:3], v[238:239]
	v_exp_f32_e32 v232, v232
	v_exp_f32_e32 v233, v233
	v_exp_f32_e32 v234, v234
	v_exp_f32_e32 v235, v235
	v_exp_f32_e32 v236, v236
	v_exp_f32_e32 v237, v237
	v_exp_f32_e32 v238, v238
	v_exp_f32_e32 v239, v239
	v_pk_add_f32 v[232:233], v[232:233], v[244:245]
	v_pk_add_f32 v[234:235], v[234:235], v[244:245]
	v_pk_add_f32 v[236:237], v[236:237], v[244:245]
	v_pk_add_f32 v[238:239], v[238:239], v[244:245]
	v_rcp_f32_e32 v232, v232
	v_rcp_f32_e32 v233, v233
	v_rcp_f32_e32 v234, v234
	v_rcp_f32_e32 v235, v235
	v_rcp_f32_e32 v236, v236
	v_rcp_f32_e32 v237, v237
	v_rcp_f32_e32 v238, v238
	v_rcp_f32_e32 v239, v239
	v_pk_mul_f32 v[232:233], v[4:5], v[232:233]
	v_pk_mul_f32 v[234:235], v[6:7], v[234:235]
	v_pk_mul_f32 v[236:237], v[0:1], v[236:237]
	v_pk_mul_f32 v[238:239], v[2:3], v[238:239]
	v_cvt_pk_bf16_f32 v246, v232, v233
	v_cvt_pk_bf16_f32 v247, v234, v235
	v_cvt_pk_bf16_f32 v248, v236, v237
	v_cvt_pk_bf16_f32 v249, v238, v239
	global_store_dwordx4 v[250:251], v[246:249], off offset:256
	s_andn2_b64 vcc, exec, s[6:7]
	s_mov_b64 s[6:7], -1
	s_cbranch_vccnz .LBB0_182
	s_branch .LBB0_274
